# stick-breaking attention task: V-row to lane remap so each output row is one packed bf16x2 dword store per lane (16 dword stores instead of 32 short stores), native packed convert
# speedup vs baseline: 1.0080x; 1.0027x over previous
; __device__ __forceinline__ bf16_t f2bf(float f) { unsigned u = __builtin_bit_cast(unsigned, f); return (bf16_t)((u + 0x7fffu + ((u >> 16) & 1u)) >> 16); }
; __device__ __forceinline__ int crow(int r, int hi) { return (r & 3) + 8 * (r >> 2) + 4 * hi; }
; __device__ __forceinline__ void sb_task(int task, const bf16_t* Q, const bf16_t* Kb, const bf16_t* Vt, bf16_t* MIX, float* ss_sb, int lane, bool do_atomic = true) {
;     const int r32 = lane & 31, hi = lane >> 5;
;     const int qb = task & 255, h = (task >> 8) & 7, b = task >> 11;
;     const size_t rowbase = (size_t)b * SEQ; const int q0 = qb * 32;
;     bf16x8 qf[4];
;     { const bf16_t* qp = Q + (rowbase + q0 + r32) * 512 + h * 64 + hi * 8;
; #pragma unroll
;       for (int ks = 0; ks < 4; ++ks) qf[ks] = *(const bf16x8*)(qp + ks * 16); }
;     f32x16 o0, o1;
; #pragma unroll
;     for (int r = 0; r < 16; ++r) { o0[r] = 0.f; o1[r] = 0.f; }
;     float R = 0.f;
;     const bf16_t* vt = Vt + (size_t)(b * 8 + h) * 64 * SEQ;
;     for (int k0 = q0; k0 >= 0; k0 -= 32) {
;         const bf16_t* kp = Kb + (rowbase + k0 + r32) * 512 + h * 64 + hi * 8;
;         bf16x8 kf[4];
; #pragma unroll
;         for (int ks = 0; ks < 4; ++ks) kf[ks] = *(const bf16x8*)(kp + ks * 16);
;         s16x4 vlo[2][2], vhi[2][2];
; #pragma unroll
;         for (int j = 0; j < 2; ++j)
; #pragma unroll
;             for (int db = 0; db < 2; ++db) { const bf16_t* vp = vt + (size_t)(32 * db + r32) * SEQ + k0 + 16 * j + 4 * hi; vlo[j][db] = *(const s16x4*)vp; vhi[j][db] = *(const s16x4*)(vp + 8); }
;     ...
; #pragma unroll
;     for (int r = 0; r < 16; ++r) {
;         const size_t row = rowbase + q0 + crow(r, hi);
;         MIX[row * 1024 + h * 64 + r32] = f2bf(o0[r]);
;         MIX[row * 1024 + h * 64 + 32 + r32] = f2bf(o1[r]);
;         float ss = o0[r] * o0[r] + o1[r] * o1[r];
;         ss += xshfl<1>(ss); ss += xshfl<2>(ss); ss += xshfl<4>(ss); ss += xshfl<8>(ss); ss += xshfl<16>(ss);
;         if (r32 == 0 && do_atomic) atomicAdd(ss_sb + row, ss);
.LBB0_325:
	s_mov_b64 s[40:41], 0xb800000
	s_or_b64 exec, exec, s[0:1]
	v_readlane_b32 s0, v215, 40
	s_cmpk_lt_i32 s54, 0x1000
	v_readlane_b32 s1, v215, 41
	s_cselect_b64 s[2:3], -1, 0
	s_mul_i32 s0, s0, 0x18000
	s_mov_b32 s1, s97
	v_writelane_b32 v215, s0, 45
	s_and_b64 vcc, exec, s[2:3]
	s_waitcnt lgkmcnt(0)
	s_barrier
	v_writelane_b32 v215, s1, 46
	v_mbcnt_lo_u32_b32 v0, -1, 0
	v_mbcnt_hi_u32_b32 v0, -1, v0
	s_cbranch_vccz .LBB0_367
	v_readlane_b32 s0, v215, 45
	v_readlane_b32 s1, v215, 46
	s_lshl_b64 s[0:1], s[0:1], 2
	v_ashrrev_i32_e32 v1, 5, v0
	s_add_u32 s0, s42, s0
	v_lshlrev_b32_e32 v82, 3, v1
	s_addc_u32 s1, s43, s1
	v_ashrrev_i32_e32 v83, 31, v82
	v_lshlrev_b32_e32 v86, 2, v1
	s_add_u32 s46, s0, 0x10000
	v_lshlrev_b64 v[2:3], 1, v[82:83]
	v_ashrrev_i32_e32 v87, 31, v86
	s_addc_u32 s47, s1, 0
	v_and_b32_e32 v80, 31, v0
	v_lshl_add_u64 v[4:5], s[42:43], 0, v[2:3]
	s_mov_b64 s[0:1], 0x7000000
	v_lshlrev_b64 v[6:7], 2, v[86:87]
	v_lshl_add_u64 v[84:85], v[4:5], 0, s[0:1]
	v_lshlrev_b32_e32 v4, 14, v80
	v_lshl_add_u64 v[8:9], s[42:43], 0, v[6:7]
	s_mov_b64 s[0:1], 0x8000000
	v_lshlrev_b32_e32 v156, 2, v80
	s_add_u32 s88, s42, 0x6000000
	v_lshl_add_u64 v[88:89], v[8:9], 0, s[0:1]
	v_cmp_gt_u32_e64 s[4:5], 32, v0
	v_or_b32_e32 v0, 0x2000, v4
	v_or_b32_e32 v90, 1, v86
	v_or_b32_e32 v92, 2, v86
	v_or_b32_e32 v94, 3, v86
	v_add_u32_e32 v96, 8, v86
	v_add_u32_e32 v98, 11, v86
	v_add_u32_e32 v100, 9, v86
	v_add_u32_e32 v102, 16, v86
	v_add_u32_e32 v104, 10, v86
	v_add_u32_e32 v106, 17, v86
	v_add_u32_e32 v108, 18, v86
	v_add_u32_e32 v110, 19, v86
	v_add_u32_e32 v112, 24, v86
	v_add_u32_e32 v114, 25, v86
	v_add_u32_e32 v116, 26, v86
	v_add_u32_e32 v118, 27, v86
	v_lshl_add_u64 v[8:9], s[42:43], 0, v[156:157]
	v_lshlrev_b32_e32 v156, 15, v80
	s_mov_b64 s[48:49], 0x7000040
	s_addc_u32 s89, s43, 0
	v_mov_b32_e32 v81, v157
	v_cmp_eq_u32_e64 s[0:1], 0, v214
	v_cmp_lt_i32_e64 s[6:7], v86, v80
	v_cmp_lt_i32_e64 s[8:9], v90, v80
	v_cmp_lt_i32_e64 s[10:11], v92, v80
	v_cmp_lt_i32_e64 s[12:13], v94, v80
	v_cmp_lt_i32_e64 s[14:15], v96, v80
	v_cmp_lt_i32_e64 s[16:17], v98, v80
	v_cmp_lt_i32_e64 s[18:19], v102, v80
	v_cmp_lt_i32_e64 s[20:21], v100, v80
	v_cmp_lt_i32_e64 s[22:23], v106, v80
	v_cmp_lt_i32_e64 s[24:25], v104, v80
	v_cmp_lt_i32_e64 s[26:27], v108, v80
	v_cmp_lt_i32_e64 s[28:29], v110, v80
	v_cmp_lt_i32_e64 s[30:31], v112, v80
	v_cmp_lt_i32_e64 s[34:35], v114, v80
	v_cmp_lt_i32_e64 s[36:37], v116, v80
	v_cmp_lt_i32_e64 s[38:39], v118, v80
	v_lshl_add_u64 v[120:121], v[8:9], 0, s[40:41]
	v_cmp_eq_u32_e64 s[40:41], 0, v80
	v_ashrrev_i32_e32 v91, 31, v90
	v_ashrrev_i32_e32 v93, 31, v92
	v_ashrrev_i32_e32 v95, 31, v94
	v_ashrrev_i32_e32 v97, 31, v96
	v_ashrrev_i32_e32 v101, 31, v100
	v_ashrrev_i32_e32 v105, 31, v104
	v_ashrrev_i32_e32 v99, 31, v98
	v_ashrrev_i32_e32 v103, 31, v102
	v_ashrrev_i32_e32 v107, 31, v106
	v_ashrrev_i32_e32 v109, 31, v108
	v_ashrrev_i32_e32 v111, 31, v110
	v_ashrrev_i32_e32 v113, 31, v112
	v_ashrrev_i32_e32 v115, 31, v114
	v_ashrrev_i32_e32 v117, 31, v116
	v_ashrrev_i32_e32 v119, 31, v118
	v_lshl_add_u64 v[122:123], v[156:157], 0, v[6:7]
	s_lshl_b32 s55, s54, 5
	v_lshl_add_u64 v[124:125], v[2:3], 0, s[48:49]
	v_lshlrev_b32_e32 v156, 1, v4
	v_lshlrev_b32_e32 v126, 1, v0
	s_mov_b32 s56, s54
	s_branch .LBB0_328

; __device__ __forceinline__ float ex2(float x) { return __builtin_amdgcn_exp2f(x); }
; __device__ __forceinline__ float lg2(float x) { return __builtin_amdgcn_logf(x); }
; __device__ __forceinline__ int crow(int r, int hi) { return (r & 3) + 8 * (r >> 2) + 4 * hi; }
; #define MFMA32(a, b, c) __builtin_amdgcn_mfma_f32_32x32x16_bf16((a), (b), (c), 0, 0, 0)
; __device__ __forceinline__ void sb_task(int task, const bf16_t* Q, const bf16_t* Kb, const bf16_t* Vt, bf16_t* MIX, float* ss_sb, int lane, bool do_atomic = true) {
;     ...
;     for (int k0 = q0; k0 >= 0; k0 -= 32) {
;         const bf16_t* kp = Kb + (rowbase + k0 + r32) * 512 + h * 64 + hi * 8;
;         bf16x8 kf[4];
; #pragma unroll
;         for (int ks = 0; ks < 4; ++ks) kf[ks] = *(const bf16x8*)(kp + ks * 16);
;         s16x4 vlo[2][2], vhi[2][2];
; #pragma unroll
;         for (int j = 0; j < 2; ++j)
; #pragma unroll
;             for (int db = 0; db < 2; ++db) { const bf16_t* vp = vt + (size_t)(32 * db + r32) * SEQ + k0 + 16 * j + 4 * hi; vlo[j][db] = *(const s16x4*)vp; vhi[j][db] = *(const s16x4*)(vp + 8); }
;         f32x16 s;
; #pragma unroll
;         for (int r = 0; r < 16; ++r) s[r] = 0.f;
; #pragma unroll
;         for (int ks = 0; ks < 4; ++ks) s = MFMA32(kf[ks], qf[ks], s);
;         const bool diag = (k0 == q0);
;         float Lr[16];
; #pragma unroll
;         for (int r = 0; r < 16; ++r) {
;             const float z = s[r];
;             float Lv = fminf(-z, 0.f) - lg2(1.f + ex2(-fabsf(z)));
;             if (diag && crow(r, hi) >= r32) Lv = 0.f;
;             Lr[r] = Lv;
;         }
;         float tot[4], oth[4], pr[4];
; #pragma unroll
;         for (int G = 0; G < 4; ++G) { Lr[4 * G + 2] += Lr[4 * G + 3]; Lr[4 * G + 1] += Lr[4 * G + 2]; Lr[4 * G] += Lr[4 * G + 1]; tot[G] = Lr[4 * G]; }
; #pragma unroll
;         for (int G = 0; G < 4; ++G) { oth[G] = xshfl<32>(tot[G]); pr[G] = tot[G] + oth[G]; }
;         float off[4];
;         { const float sp3 = 0.f, sp2 = pr[3], sp1 = sp2 + pr[2], sp0 = sp1 + pr[1];
;           off[3] = sp3 + R; off[2] = sp2 + R; off[1] = sp1 + R; off[0] = sp0 + R;
;           if (hi == 0) { off[0] += oth[0]; off[1] += oth[1]; off[2] += oth[2]; off[3] += oth[3]; }
;           R += sp0 + pr[0]; }
.LBB0_333:
	v_lshl_add_u64 v[36:37], s[42:43], 0, v[130:131]
	global_load_dwordx4 v[32:35], v[36:37], off offset:-64
	global_load_dwordx4 v[132:135], v[36:37], off offset:-32
	global_load_dwordx4 v[136:139], v[36:37], off
	global_load_dwordx4 v[140:143], v[36:37], off offset:32
	v_lshl_add_u64 v[36:37], s[42:43], 0, v[128:129]
	v_add_co_u32_e32 v38, vcc, 0x8000000, v36
	s_nop 1
	v_addc_co_u32_e32 v39, vcc, 0, v37, vcc
	v_add_co_u32_e32 v36, vcc, 0x8004000, v36
	global_load_dwordx4 v[76:79], v[38:39], off
	v_addc_co_u32_e32 v37, vcc, 0, v37, vcc
	global_load_dwordx4 v[72:75], v[36:37], off
	global_load_dwordx4 v[68:71], v[38:39], off offset:32
	global_load_dwordx4 v[64:67], v[36:37], off offset:32
	s_waitcnt vmcnt(7)
	v_mfma_f32_32x32x16_bf16 v[32:47], v[32:35], v[48:51], 0
	s_waitcnt vmcnt(6)
	v_mfma_f32_32x32x16_bf16 v[32:47], v[132:135], v[52:55], v[32:47]
	s_waitcnt vmcnt(5)
	v_mfma_f32_32x32x16_bf16 v[32:47], v[136:139], v[56:59], v[32:47]
	s_waitcnt vmcnt(4)
	v_mfma_f32_32x32x16_bf16 v[32:47], v[140:143], v[60:63], v[32:47]
	s_nop 11
	v_exp_f32_e64 v133, -|v32|
	v_max_f32_e64 v132, -v32, -v32
	v_min_f32_e32 v132, 0, v132
	v_exp_f32_e64 v135, -|v39|
	v_add_f32_e32 v133, 1.0, v133
	v_log_f32_e32 v133, v133
	v_exp_f32_e64 v147, -|v46|
	v_add_f32_e32 v135, 1.0, v135
	v_log_f32_e32 v137, v135
	v_sub_f32_e32 v134, v132, v133
	v_exp_f32_e64 v133, -|v33|
	v_max_f32_e64 v132, -v33, -v33
	v_min_f32_e32 v132, 0, v132
	v_max_f32_e64 v135, -v40, -v40
	v_add_f32_e32 v133, 1.0, v133
	v_log_f32_e32 v133, v133
	v_exp_f32_e64 v149, -|v47|
	v_exp_f32_e64 v138, -|v44|
	v_exp_f32_e64 v142, -|v45|
	v_sub_f32_e32 v144, v132, v133
	v_exp_f32_e64 v133, -|v34|
	v_max_f32_e64 v132, -v34, -v34
	v_min_f32_e32 v132, 0, v132
	v_add_f32_e32 v147, 1.0, v147
	v_add_f32_e32 v133, 1.0, v133
	v_log_f32_e32 v133, v133
	v_add_f32_e32 v149, 1.0, v149
	v_log_f32_e32 v148, v147
	v_log_f32_e32 v149, v149
	v_sub_f32_e32 v150, v132, v133
	v_exp_f32_e64 v133, -|v35|
	v_max_f32_e64 v132, -v35, -v35
	v_min_f32_e32 v132, 0, v132
	v_max_f32_e64 v146, -v46, -v46
	v_add_f32_e32 v133, 1.0, v133
	v_log_f32_e32 v133, v133
	v_max_f32_e64 v147, -v47, -v47
	v_add_f32_e32 v138, 1.0, v138
	v_add_f32_e32 v142, 1.0, v142
	v_sub_f32_e32 v152, v132, v133
	v_exp_f32_e64 v133, -|v36|
	v_max_f32_e64 v132, -v36, -v36
	v_min_f32_e32 v132, 0, v132
	v_add_f32_e32 v155, v150, v152
	v_add_f32_e32 v133, 1.0, v133
	v_log_f32_e32 v133, v133
	v_add_f32_e32 v166, v144, v155
	v_add_f32_e32 v153, v134, v166
	v_min_f32_e32 v146, 0, v146
	v_sub_f32_e32 v151, v132, v133
	v_exp_f32_e64 v133, -|v37|
	v_max_f32_e64 v132, -v37, -v37
	v_min_f32_e32 v132, 0, v132
	v_min_f32_e32 v147, 0, v147
	v_add_f32_e32 v133, 1.0, v133
	v_log_f32_e32 v133, v133
	v_mov_b32_e32 v134, v153
	v_log_f32_e32 v138, v138
	v_log_f32_e32 v142, v142
	v_sub_f32_e32 v158, v132, v133
	v_exp_f32_e64 v133, -|v38|
	v_max_f32_e64 v132, -v38, -v38
	v_min_f32_e32 v132, 0, v132
	v_pk_add_f32 v[146:147], v[146:147], v[148:149] neg_lo:[0,1] neg_hi:[0,1]
	v_add_f32_e32 v133, 1.0, v133
	v_log_f32_e32 v136, v133
	v_max_f32_e64 v133, -v39, -v39
	v_min_f32_e32 v133, 0, v133
	v_max_f32_e64 v140, -v45, -v45
	v_pk_add_f32 v[132:133], v[132:133], v[136:137] neg_lo:[0,1] neg_hi:[0,1]
	v_min_f32_e32 v137, 0, v135
	v_exp_f32_e64 v135, -|v40|
	v_exp_f32_e64 v136, -|v42|
	v_add_f32_e32 v154, v132, v133
	v_add_f32_e32 v167, v158, v154
	v_add_f32_e32 v135, 1.0, v135
	v_log_f32_e32 v139, v135
	v_max_f32_e64 v135, -v41, -v41
	v_min_f32_e32 v141, 0, v135
	v_exp_f32_e64 v135, -|v41|
	v_add_f32_e32 v136, 1.0, v136
	v_log_f32_e32 v136, v136
	v_mov_b32_e32 v132, v153
	v_add_f32_e32 v135, 1.0, v135
	v_log_f32_e32 v143, v135
	v_max_f32_e64 v135, -v42, -v42
	v_min_f32_e32 v135, 0, v135
	v_sub_f32_e32 v145, v135, v136
	v_exp_f32_e64 v136, -|v43|
	v_max_f32_e64 v135, -v43, -v43
	v_add_f32_e32 v148, v151, v167
	v_permlane32_swap_b32_e32 v132, v134
	v_add_f32_e32 v136, 1.0, v136
	v_log_f32_e32 v136, v136
	v_min_f32_e32 v135, 0, v135
	v_cndmask_b32_e64 v132, v132, v134, s[0:1]
	v_mov_b32_e32 v134, v148
	v_mov_b32_e32 v144, v148
	v_sub_f32_e32 v135, v135, v136
	v_max_f32_e64 v136, -v44, -v44
	v_permlane32_swap_b32_e32 v134, v144
	v_min_f32_e32 v136, 0, v136
	v_min_f32_e32 v140, 0, v140
	v_cndmask_b32_e64 v150, v134, v144, s[0:1]
	v_mov_b32_e32 v144, v146
	v_mov_b32_e32 v134, v147
	v_pk_add_f32 v[168:169], v[136:137], v[138:139] neg_lo:[0,1] neg_hi:[0,1]
	v_pk_add_f32 v[138:139], v[140:141], v[142:143] neg_lo:[0,1] neg_hi:[0,1]
	v_pk_add_f32 v[136:137], v[144:145], v[134:135]
	s_nop 0
	v_pk_add_f32 v[138:139], v[138:139], v[136:137]
	s_nop 0
	v_pk_add_f32 v[140:141], v[168:169], v[138:139]
	s_nop 0
	v_mov_b32_e32 v134, v141
	v_mov_b32_e32 v142, v141
	v_mov_b32_e32 v144, v140
	v_mov_b32_e32 v145, v140
	v_permlane32_swap_b32_e32 v134, v142
	s_nop 0
	v_permlane32_swap_b32_e32 v144, v145
	v_cndmask_b32_e64 v143, v134, v142, s[0:1]
	v_cndmask_b32_e64 v142, v144, v145, s[0:1]
	v_pk_add_f32 v[168:169], v[140:141], v[142:143]
	v_add_f32_e32 v144, 0, v127
	v_mov_b32_e32 v149, v168
	v_mov_b32_e32 v151, v169
	v_pk_add_f32 v[170:171], v[148:149], v[150:151]
	v_add_f32_e32 v145, v127, v168
	v_add_f32_e32 v134, v170, v171
	v_add_f32_e32 v146, v127, v171
	v_add_f32_e32 v149, v127, v134
	s_and_saveexec_b64 s[48:49], s[4:5]
	s_cbranch_execz .LBB0_332
	v_add_f32_e32 v144, v144, v142
	v_add_f32_e32 v145, v145, v143
	v_add_f32_e32 v146, v146, v150
	v_add_f32_e32 v149, v149, v132
	s_branch .LBB0_332
; __device__ __forceinline__ bf16_t f2bf(float f) { unsigned u = __builtin_bit_cast(unsigned, f); return (bf16_t)((u + 0x7fffu + ((u >> 16) & 1u)) >> 16); }
; __device__ __forceinline__ int crow(int r, int hi) { return (r & 3) + 8 * (r >> 2) + 4 * hi; }
; __device__ __forceinline__ void sb_task(int task, const bf16_t* Q, const bf16_t* Kb, const bf16_t* Vt, bf16_t* MIX, float* ss_sb, int lane, bool do_atomic = true) {
;     ...
; #pragma unroll
;     for (int r = 0; r < 16; ++r) {
;         const size_t row = rowbase + q0 + crow(r, hi);
;         MIX[row * 1024 + h * 64 + r32] = f2bf(o0[r]);
;         MIX[row * 1024 + h * 64 + 32 + r32] = f2bf(o1[r]);
;         float ss = o0[r] * o0[r] + o1[r] * o1[r];
;         ss += xshfl<1>(ss); ss += xshfl<2>(ss); ss += xshfl<4>(ss); ss += xshfl<8>(ss); ss += xshfl<16>(ss);
;         if (r32 == 0 && do_atomic) atomicAdd(ss_sb + row, ss);
.LBB0_335:
	s_lshl_b32 s48, s57, 6
	s_lshl_b32 s96, s48, 1
	v_lshl_add_u64 v[34:35], s[90:91], 0, v[86:87]
	s_nop 5
	s_nop 7
	v_lshl_add_u64 v[32:33], v[120:121], 0, s[96:97]
	v_lshl_add_u64 v[34:35], s[90:91], 0, v[86:87]
	v_cvt_pk_bf16_f32 v38, v0, v16
	v_lshlrev_b64 v[36:37], 11, v[34:35]
	v_lshl_add_u64 v[36:37], v[32:33], 0, v[36:37]
	global_store_dword v[36:37], v38, off
	v_mul_f32_e32 v48, v16, v16
	v_fmac_f32_e32 v48, v0, v0
	v_lshl_add_u64 v[34:35], s[90:91], 0, v[90:91]
	v_cvt_pk_bf16_f32 v42, v1, v17
	v_lshlrev_b64 v[40:41], 11, v[34:35]
	v_lshl_add_u64 v[40:41], v[32:33], 0, v[40:41]
	global_store_dword v[40:41], v42, off
	v_mul_f32_e32 v49, v17, v17
	v_fmac_f32_e32 v49, v1, v1
	v_lshl_add_u64 v[34:35], s[90:91], 0, v[92:93]
	v_cvt_pk_bf16_f32 v46, v2, v18
	v_lshlrev_b64 v[44:45], 11, v[34:35]
	v_lshl_add_u64 v[44:45], v[32:33], 0, v[44:45]
	global_store_dword v[44:45], v46, off
	v_mul_f32_e32 v50, v18, v18
	v_fmac_f32_e32 v50, v2, v2
	v_lshl_add_u64 v[34:35], s[90:91], 0, v[94:95]
	v_cvt_pk_bf16_f32 v38, v3, v19
	v_lshlrev_b64 v[36:37], 11, v[34:35]
	v_lshl_add_u64 v[36:37], v[32:33], 0, v[36:37]
	global_store_dword v[36:37], v38, off
	v_mul_f32_e32 v51, v19, v19
	v_fmac_f32_e32 v51, v3, v3
	v_lshl_add_u64 v[34:35], s[90:91], 0, v[96:97]
	v_cvt_pk_bf16_f32 v42, v4, v20
	v_lshlrev_b64 v[40:41], 11, v[34:35]
	v_lshl_add_u64 v[40:41], v[32:33], 0, v[40:41]
	global_store_dword v[40:41], v42, off
	v_mul_f32_e32 v52, v20, v20
	v_fmac_f32_e32 v52, v4, v4
	v_lshl_add_u64 v[34:35], s[90:91], 0, v[100:101]
	v_cvt_pk_bf16_f32 v46, v5, v21
	v_lshlrev_b64 v[44:45], 11, v[34:35]
	v_lshl_add_u64 v[44:45], v[32:33], 0, v[44:45]
	global_store_dword v[44:45], v46, off
	v_mul_f32_e32 v53, v21, v21
	v_fmac_f32_e32 v53, v5, v5
	v_lshl_add_u64 v[34:35], s[90:91], 0, v[104:105]
	v_cvt_pk_bf16_f32 v38, v6, v22
	v_lshlrev_b64 v[36:37], 11, v[34:35]
	v_lshl_add_u64 v[36:37], v[32:33], 0, v[36:37]
	global_store_dword v[36:37], v38, off
	v_mul_f32_e32 v54, v22, v22
	v_fmac_f32_e32 v54, v6, v6
	v_lshl_add_u64 v[34:35], s[90:91], 0, v[98:99]
	v_cvt_pk_bf16_f32 v42, v7, v23
	v_lshlrev_b64 v[40:41], 11, v[34:35]
	v_lshl_add_u64 v[40:41], v[32:33], 0, v[40:41]
	global_store_dword v[40:41], v42, off
	v_mul_f32_e32 v55, v23, v23
	v_fmac_f32_e32 v55, v7, v7
	v_lshl_add_u64 v[34:35], s[90:91], 0, v[102:103]
	v_cvt_pk_bf16_f32 v46, v8, v24
	v_lshlrev_b64 v[44:45], 11, v[34:35]
	v_lshl_add_u64 v[44:45], v[32:33], 0, v[44:45]
	global_store_dword v[44:45], v46, off
	v_mul_f32_e32 v56, v24, v24
	v_fmac_f32_e32 v56, v8, v8
	v_lshl_add_u64 v[34:35], s[90:91], 0, v[106:107]
	v_cvt_pk_bf16_f32 v38, v9, v25
	v_lshlrev_b64 v[36:37], 11, v[34:35]
	v_lshl_add_u64 v[36:37], v[32:33], 0, v[36:37]
	global_store_dword v[36:37], v38, off
	v_mul_f32_e32 v57, v25, v25
	v_fmac_f32_e32 v57, v9, v9
	v_lshl_add_u64 v[34:35], s[90:91], 0, v[108:109]
	v_cvt_pk_bf16_f32 v42, v10, v26
	v_lshlrev_b64 v[40:41], 11, v[34:35]
	v_lshl_add_u64 v[40:41], v[32:33], 0, v[40:41]
	global_store_dword v[40:41], v42, off
	v_mul_f32_e32 v58, v26, v26
	v_fmac_f32_e32 v58, v10, v10
	v_lshl_add_u64 v[34:35], s[90:91], 0, v[110:111]
	v_cvt_pk_bf16_f32 v46, v11, v27
	v_lshlrev_b64 v[44:45], 11, v[34:35]
	v_lshl_add_u64 v[44:45], v[32:33], 0, v[44:45]
	global_store_dword v[44:45], v46, off
	v_mul_f32_e32 v59, v27, v27
	v_fmac_f32_e32 v59, v11, v11
	v_lshl_add_u64 v[34:35], s[90:91], 0, v[112:113]
	v_cvt_pk_bf16_f32 v38, v12, v28
	v_lshlrev_b64 v[36:37], 11, v[34:35]
	v_lshl_add_u64 v[36:37], v[32:33], 0, v[36:37]
	global_store_dword v[36:37], v38, off
	v_mul_f32_e32 v60, v28, v28
	v_fmac_f32_e32 v60, v12, v12
	v_lshl_add_u64 v[34:35], s[90:91], 0, v[114:115]
	v_cvt_pk_bf16_f32 v42, v13, v29
	v_lshlrev_b64 v[40:41], 11, v[34:35]
	v_lshl_add_u64 v[40:41], v[32:33], 0, v[40:41]
	global_store_dword v[40:41], v42, off
	v_mul_f32_e32 v61, v29, v29
	v_fmac_f32_e32 v61, v13, v13
	v_lshl_add_u64 v[34:35], s[90:91], 0, v[116:117]
	v_cvt_pk_bf16_f32 v46, v14, v30
	v_lshlrev_b64 v[44:45], 11, v[34:35]
	v_lshl_add_u64 v[44:45], v[32:33], 0, v[44:45]
	global_store_dword v[44:45], v46, off
	v_mul_f32_e32 v62, v30, v30
	v_fmac_f32_e32 v62, v14, v14
	v_lshl_add_u64 v[34:35], s[90:91], 0, v[118:119]
	v_cvt_pk_bf16_f32 v38, v15, v31
	v_lshlrev_b64 v[36:37], 11, v[34:35]
	v_lshl_add_u64 v[36:37], v[32:33], 0, v[36:37]
	global_store_dword v[36:37], v38, off
	v_mul_f32_e32 v63, v31, v31
	v_fmac_f32_e32 v63, v15, v15
	ds_swizzle_b32 v64, v48 offset:swizzle(SWAP,1)
	ds_swizzle_b32 v65, v49 offset:swizzle(SWAP,1)
	ds_swizzle_b32 v66, v50 offset:swizzle(SWAP,1)
	ds_swizzle_b32 v67, v51 offset:swizzle(SWAP,1)
	ds_swizzle_b32 v68, v52 offset:swizzle(SWAP,1)
	ds_swizzle_b32 v69, v53 offset:swizzle(SWAP,1)
	ds_swizzle_b32 v70, v54 offset:swizzle(SWAP,1)
	ds_swizzle_b32 v71, v55 offset:swizzle(SWAP,1)
	ds_swizzle_b32 v72, v56 offset:swizzle(SWAP,1)
	s_waitcnt lgkmcnt(8)
	v_add_f32_e32 v48, v48, v64
	ds_swizzle_b32 v73, v57 offset:swizzle(SWAP,1)
	s_waitcnt lgkmcnt(8)
	v_add_f32_e32 v49, v49, v65
	ds_swizzle_b32 v74, v58 offset:swizzle(SWAP,1)
	s_waitcnt lgkmcnt(8)
	v_add_f32_e32 v50, v50, v66
	ds_swizzle_b32 v75, v59 offset:swizzle(SWAP,1)
	s_waitcnt lgkmcnt(8)
	v_add_f32_e32 v51, v51, v67
	ds_swizzle_b32 v76, v60 offset:swizzle(SWAP,1)
	s_waitcnt lgkmcnt(8)
	v_add_f32_e32 v52, v52, v68
	ds_swizzle_b32 v77, v61 offset:swizzle(SWAP,1)
	s_waitcnt lgkmcnt(8)
	v_add_f32_e32 v53, v53, v69
	ds_swizzle_b32 v78, v62 offset:swizzle(SWAP,1)
	s_waitcnt lgkmcnt(8)
	v_add_f32_e32 v54, v54, v70
	ds_swizzle_b32 v79, v63 offset:swizzle(SWAP,1)
	s_waitcnt lgkmcnt(8)
	v_add_f32_e32 v55, v55, v71
	s_waitcnt lgkmcnt(7)
	v_add_f32_e32 v56, v56, v72
	s_waitcnt lgkmcnt(6)
; __device__ __forceinline__ void sb_task(int task, const bf16_t* Q, const bf16_t* Kb, const bf16_t* Vt, bf16_t* MIX, float* ss_sb, int lane, bool do_atomic = true) {
;     ...
;         float ss = o0[r] * o0[r] + o1[r] * o1[r];
;         ss += xshfl<1>(ss); ss += xshfl<2>(ss); ss += xshfl<4>(ss); ss += xshfl<8>(ss); ss += xshfl<16>(ss);
;         if (r32 == 0 && do_atomic) atomicAdd(ss_sb + row, ss);
	v_add_f32_e32 v57, v57, v73
	s_waitcnt lgkmcnt(5)
	v_add_f32_e32 v58, v58, v74
	s_waitcnt lgkmcnt(4)
	v_add_f32_e32 v59, v59, v75
	s_waitcnt lgkmcnt(3)
	v_add_f32_e32 v60, v60, v76
	s_waitcnt lgkmcnt(2)
	v_add_f32_e32 v61, v61, v77
	s_waitcnt lgkmcnt(1)
	v_add_f32_e32 v62, v62, v78
	s_waitcnt lgkmcnt(0)
	v_add_f32_e32 v63, v63, v79
	ds_swizzle_b32 v64, v48 offset:swizzle(SWAP,2)
	ds_swizzle_b32 v65, v49 offset:swizzle(SWAP,2)
	ds_swizzle_b32 v66, v50 offset:swizzle(SWAP,2)
	ds_swizzle_b32 v67, v51 offset:swizzle(SWAP,2)
	ds_swizzle_b32 v68, v52 offset:swizzle(SWAP,2)
	ds_swizzle_b32 v69, v53 offset:swizzle(SWAP,2)
	ds_swizzle_b32 v70, v54 offset:swizzle(SWAP,2)
	ds_swizzle_b32 v71, v55 offset:swizzle(SWAP,2)
	ds_swizzle_b32 v72, v56 offset:swizzle(SWAP,2)
	s_waitcnt lgkmcnt(8)
	v_add_f32_e32 v48, v48, v64
	ds_swizzle_b32 v73, v57 offset:swizzle(SWAP,2)
	s_waitcnt lgkmcnt(8)
	v_add_f32_e32 v49, v49, v65
	ds_swizzle_b32 v74, v58 offset:swizzle(SWAP,2)
	s_waitcnt lgkmcnt(8)
	v_add_f32_e32 v50, v50, v66
	ds_swizzle_b32 v75, v59 offset:swizzle(SWAP,2)
	s_waitcnt lgkmcnt(8)
	v_add_f32_e32 v51, v51, v67
	ds_swizzle_b32 v76, v60 offset:swizzle(SWAP,2)
	s_waitcnt lgkmcnt(8)
	v_add_f32_e32 v52, v52, v68
	ds_swizzle_b32 v77, v61 offset:swizzle(SWAP,2)
	s_waitcnt lgkmcnt(8)
	v_add_f32_e32 v53, v53, v69
	ds_swizzle_b32 v78, v62 offset:swizzle(SWAP,2)
	s_waitcnt lgkmcnt(8)
	v_add_f32_e32 v54, v54, v70
	ds_swizzle_b32 v79, v63 offset:swizzle(SWAP,2)
	s_waitcnt lgkmcnt(8)
	v_add_f32_e32 v55, v55, v71
	s_waitcnt lgkmcnt(7)
	v_add_f32_e32 v56, v56, v72
	s_waitcnt lgkmcnt(6)
	v_add_f32_e32 v57, v57, v73
	s_waitcnt lgkmcnt(5)
	v_add_f32_e32 v58, v58, v74
	s_waitcnt lgkmcnt(4)
	v_add_f32_e32 v59, v59, v75
	s_waitcnt lgkmcnt(3)
	v_add_f32_e32 v60, v60, v76
	s_waitcnt lgkmcnt(2)
	v_add_f32_e32 v61, v61, v77
	s_waitcnt lgkmcnt(1)
	v_add_f32_e32 v62, v62, v78
	s_waitcnt lgkmcnt(0)
	v_add_f32_e32 v63, v63, v79
	ds_swizzle_b32 v64, v48 offset:swizzle(SWAP,4)
	ds_swizzle_b32 v65, v49 offset:swizzle(SWAP,4)
	ds_swizzle_b32 v66, v50 offset:swizzle(SWAP,4)
	ds_swizzle_b32 v67, v51 offset:swizzle(SWAP,4)
	ds_swizzle_b32 v68, v52 offset:swizzle(SWAP,4)
	ds_swizzle_b32 v69, v53 offset:swizzle(SWAP,4)
	ds_swizzle_b32 v70, v54 offset:swizzle(SWAP,4)
	ds_swizzle_b32 v71, v55 offset:swizzle(SWAP,4)
	ds_swizzle_b32 v72, v56 offset:swizzle(SWAP,4)
	s_waitcnt lgkmcnt(8)
	v_add_f32_e32 v48, v48, v64
	ds_swizzle_b32 v73, v57 offset:swizzle(SWAP,4)
	s_waitcnt lgkmcnt(8)
	v_add_f32_e32 v49, v49, v65
	ds_swizzle_b32 v74, v58 offset:swizzle(SWAP,4)
	s_waitcnt lgkmcnt(8)
	v_add_f32_e32 v50, v50, v66
	ds_swizzle_b32 v75, v59 offset:swizzle(SWAP,4)
	s_waitcnt lgkmcnt(8)
	v_add_f32_e32 v51, v51, v67
	ds_swizzle_b32 v76, v60 offset:swizzle(SWAP,4)
	s_waitcnt lgkmcnt(8)
	v_add_f32_e32 v52, v52, v68
	ds_swizzle_b32 v77, v61 offset:swizzle(SWAP,4)
	s_waitcnt lgkmcnt(8)
	v_add_f32_e32 v53, v53, v69
	ds_swizzle_b32 v78, v62 offset:swizzle(SWAP,4)
	s_waitcnt lgkmcnt(8)
	v_add_f32_e32 v54, v54, v70
	ds_swizzle_b32 v79, v63 offset:swizzle(SWAP,4)
	s_waitcnt lgkmcnt(8)
	v_add_f32_e32 v55, v55, v71
	s_waitcnt lgkmcnt(7)
	v_add_f32_e32 v56, v56, v72
	s_waitcnt lgkmcnt(6)
	v_add_f32_e32 v57, v57, v73
	s_waitcnt lgkmcnt(5)
	v_add_f32_e32 v58, v58, v74
	s_waitcnt lgkmcnt(4)
	v_add_f32_e32 v59, v59, v75
	s_waitcnt lgkmcnt(3)
	v_add_f32_e32 v60, v60, v76
	s_waitcnt lgkmcnt(2)
	v_add_f32_e32 v61, v61, v77
	s_waitcnt lgkmcnt(1)
	v_add_f32_e32 v62, v62, v78
	s_waitcnt lgkmcnt(0)
	v_add_f32_e32 v63, v63, v79
	ds_swizzle_b32 v64, v48 offset:swizzle(SWAP,8)
	ds_swizzle_b32 v65, v49 offset:swizzle(SWAP,8)
	ds_swizzle_b32 v66, v50 offset:swizzle(SWAP,8)
	ds_swizzle_b32 v67, v51 offset:swizzle(SWAP,8)
	ds_swizzle_b32 v68, v52 offset:swizzle(SWAP,8)
	ds_swizzle_b32 v69, v53 offset:swizzle(SWAP,8)
	ds_swizzle_b32 v70, v54 offset:swizzle(SWAP,8)
	ds_swizzle_b32 v71, v55 offset:swizzle(SWAP,8)
	ds_swizzle_b32 v72, v56 offset:swizzle(SWAP,8)
	s_waitcnt lgkmcnt(8)
	v_add_f32_e32 v48, v48, v64
	ds_swizzle_b32 v73, v57 offset:swizzle(SWAP,8)
	s_waitcnt lgkmcnt(8)
	v_add_f32_e32 v49, v49, v65
	ds_swizzle_b32 v74, v58 offset:swizzle(SWAP,8)
	s_waitcnt lgkmcnt(8)
	v_add_f32_e32 v50, v50, v66
	ds_swizzle_b32 v75, v59 offset:swizzle(SWAP,8)
	s_waitcnt lgkmcnt(8)
	v_add_f32_e32 v51, v51, v67
	ds_swizzle_b32 v76, v60 offset:swizzle(SWAP,8)
	s_waitcnt lgkmcnt(8)
	v_add_f32_e32 v52, v52, v68
	ds_swizzle_b32 v77, v61 offset:swizzle(SWAP,8)
	s_waitcnt lgkmcnt(8)
	v_add_f32_e32 v53, v53, v69
	ds_swizzle_b32 v78, v62 offset:swizzle(SWAP,8)
	s_waitcnt lgkmcnt(8)
	v_add_f32_e32 v54, v54, v70
	ds_swizzle_b32 v79, v63 offset:swizzle(SWAP,8)
	s_waitcnt lgkmcnt(8)
	v_add_f32_e32 v55, v55, v71
	s_waitcnt lgkmcnt(7)
	v_add_f32_e32 v56, v56, v72
	s_waitcnt lgkmcnt(6)
	v_add_f32_e32 v57, v57, v73
	s_waitcnt lgkmcnt(5)
	v_add_f32_e32 v58, v58, v74
	s_waitcnt lgkmcnt(4)
	v_add_f32_e32 v59, v59, v75
	s_waitcnt lgkmcnt(3)
	v_add_f32_e32 v60, v60, v76
	s_waitcnt lgkmcnt(2)
	v_add_f32_e32 v61, v61, v77
	s_waitcnt lgkmcnt(1)
	v_add_f32_e32 v62, v62, v78
	s_waitcnt lgkmcnt(0)
	v_add_f32_e32 v63, v63, v79
	ds_swizzle_b32 v64, v48 offset:swizzle(SWAP,16)
	ds_swizzle_b32 v65, v49 offset:swizzle(SWAP,16)
	ds_swizzle_b32 v66, v50 offset:swizzle(SWAP,16)
	ds_swizzle_b32 v67, v51 offset:swizzle(SWAP,16)
	ds_swizzle_b32 v68, v52 offset:swizzle(SWAP,16)
	ds_swizzle_b32 v69, v53 offset:swizzle(SWAP,16)
	ds_swizzle_b32 v70, v54 offset:swizzle(SWAP,16)
	ds_swizzle_b32 v71, v55 offset:swizzle(SWAP,16)
	ds_swizzle_b32 v72, v56 offset:swizzle(SWAP,16)
	s_waitcnt lgkmcnt(8)
	v_add_f32_e32 v48, v48, v64
	ds_swizzle_b32 v73, v57 offset:swizzle(SWAP,16)
	s_waitcnt lgkmcnt(8)
	v_add_f32_e32 v49, v49, v65
	ds_swizzle_b32 v74, v58 offset:swizzle(SWAP,16)
	s_waitcnt lgkmcnt(8)
	v_add_f32_e32 v50, v50, v66
	ds_swizzle_b32 v75, v59 offset:swizzle(SWAP,16)
	s_waitcnt lgkmcnt(8)
	v_add_f32_e32 v51, v51, v67
	ds_swizzle_b32 v76, v60 offset:swizzle(SWAP,16)
	s_waitcnt lgkmcnt(8)
	v_add_f32_e32 v52, v52, v68
	ds_swizzle_b32 v77, v61 offset:swizzle(SWAP,16)
	s_waitcnt lgkmcnt(8)
	v_add_f32_e32 v53, v53, v69
	ds_swizzle_b32 v78, v62 offset:swizzle(SWAP,16)
	s_waitcnt lgkmcnt(8)
	v_add_f32_e32 v54, v54, v70
	ds_swizzle_b32 v79, v63 offset:swizzle(SWAP,16)
	s_waitcnt lgkmcnt(8)
	v_add_f32_e32 v55, v55, v71
	s_waitcnt lgkmcnt(7)
	v_add_f32_e32 v56, v56, v72
	s_waitcnt lgkmcnt(6)
	v_add_f32_e32 v57, v57, v73
	s_waitcnt lgkmcnt(5)
	v_add_f32_e32 v58, v58, v74
	s_waitcnt lgkmcnt(4)
	v_add_f32_e32 v59, v59, v75
	s_waitcnt lgkmcnt(3)
	v_add_f32_e32 v60, v60, v76
	s_waitcnt lgkmcnt(2)
	v_add_f32_e32 v61, v61, v77
	s_waitcnt lgkmcnt(1)
	v_add_f32_e32 v62, v62, v78
	s_waitcnt lgkmcnt(0)
	v_add_f32_e32 v63, v63, v79
	s_and_saveexec_b64 s[48:49], s[40:41]
	s_cbranch_execz .LBB0_327
; __device__ __forceinline__ void sb_task(int task, const bf16_t* Q, const bf16_t* Kb, const bf16_t* Vt, bf16_t* MIX, float* ss_sb, int lane, bool do_atomic = true) {
;     ...
;         float ss = o0[r] * o0[r] + o1[r] * o1[r];
;         ss += xshfl<1>(ss); ss += xshfl<2>(ss); ss += xshfl<4>(ss); ss += xshfl<8>(ss); ss += xshfl<16>(ss);
;         if (r32 == 0 && do_atomic) atomicAdd(ss_sb + row, ss);
;     }
	v_lshl_add_u64 v[34:35], s[90:91], 0, v[86:87]
	v_lshl_add_u64 v[34:35], v[34:35], 2, s[46:47]
	global_atomic_add_f32 v[34:35], v48, off
	v_lshl_add_u64 v[34:35], s[90:91], 0, v[90:91]
	v_lshl_add_u64 v[34:35], v[34:35], 2, s[46:47]
	global_atomic_add_f32 v[34:35], v49, off
	v_lshl_add_u64 v[34:35], s[90:91], 0, v[92:93]
	v_lshl_add_u64 v[34:35], v[34:35], 2, s[46:47]
	global_atomic_add_f32 v[34:35], v50, off
	v_lshl_add_u64 v[34:35], s[90:91], 0, v[94:95]
	v_lshl_add_u64 v[34:35], v[34:35], 2, s[46:47]
	global_atomic_add_f32 v[34:35], v51, off
	v_lshl_add_u64 v[34:35], s[90:91], 0, v[96:97]
	v_lshl_add_u64 v[34:35], v[34:35], 2, s[46:47]
	global_atomic_add_f32 v[34:35], v52, off
	v_lshl_add_u64 v[34:35], s[90:91], 0, v[100:101]
	v_lshl_add_u64 v[34:35], v[34:35], 2, s[46:47]
	global_atomic_add_f32 v[34:35], v53, off
	v_lshl_add_u64 v[34:35], s[90:91], 0, v[104:105]
	v_lshl_add_u64 v[34:35], v[34:35], 2, s[46:47]
	global_atomic_add_f32 v[34:35], v54, off
	v_lshl_add_u64 v[34:35], s[90:91], 0, v[98:99]
	v_lshl_add_u64 v[34:35], v[34:35], 2, s[46:47]
	global_atomic_add_f32 v[34:35], v55, off
	v_lshl_add_u64 v[34:35], s[90:91], 0, v[102:103]
	v_lshl_add_u64 v[34:35], v[34:35], 2, s[46:47]
	global_atomic_add_f32 v[34:35], v56, off
	v_lshl_add_u64 v[34:35], s[90:91], 0, v[106:107]
	v_lshl_add_u64 v[34:35], v[34:35], 2, s[46:47]
	global_atomic_add_f32 v[34:35], v57, off
	v_lshl_add_u64 v[34:35], s[90:91], 0, v[108:109]
	v_lshl_add_u64 v[34:35], v[34:35], 2, s[46:47]
	global_atomic_add_f32 v[34:35], v58, off
	v_lshl_add_u64 v[34:35], s[90:91], 0, v[110:111]
	v_lshl_add_u64 v[34:35], v[34:35], 2, s[46:47]
	global_atomic_add_f32 v[34:35], v59, off
	v_lshl_add_u64 v[34:35], s[90:91], 0, v[112:113]
	v_lshl_add_u64 v[34:35], v[34:35], 2, s[46:47]
	global_atomic_add_f32 v[34:35], v60, off
	v_lshl_add_u64 v[34:35], s[90:91], 0, v[114:115]
	v_lshl_add_u64 v[34:35], v[34:35], 2, s[46:47]
	global_atomic_add_f32 v[34:35], v61, off
	v_lshl_add_u64 v[34:35], s[90:91], 0, v[116:117]
	v_lshl_add_u64 v[34:35], v[34:35], 2, s[46:47]
	global_atomic_add_f32 v[34:35], v62, off
	v_lshl_add_u64 v[34:35], s[90:91], 0, v[118:119]
	v_lshl_add_u64 v[34:35], v[34:35], 2, s[46:47]
	global_atomic_add_f32 v[34:35], v63, off
	s_branch .LBB0_327
